# stack42 + redundant s_nop 0 removed from the six LDS-DMA issue snippets per attention step (the address VALU already separates the M0 write from the load)
# baseline (speedup 1.0000x reference)
.Li0_entry:
	v_add_u32_e32 v167, s79, v147
	v_add_u32_e32 v227, s79, v149
	v_add_u32_e32 v194, s79, v151
	v_add_u32_e32 v195, s79, v153
	ds_read_b128 v[64:67], v167
	ds_read_b128 v[188:191], v227
	ds_read_b128 v[228:231], v194
	ds_read_b128 v[184:187], v195
	ds_read_b128 v[180:183], v167 offset:128
	s_waitcnt lgkmcnt(4)
	v_mfma_f32_32x32x16_bf16 v[64:79], v[64:67], v[80:83], 0
	s_waitcnt lgkmcnt(3)
	v_mfma_f32_32x32x16_bf16 v[64:79], v[188:191], v[84:87], v[64:79]
	ds_read_b128 v[188:191], v227 offset:128
	s_mov_b64 s[54:55], 0xe404000
	s_add_i32 m0, s96, 0x8000
	v_lshl_add_u64 v[192:193], v[134:135], 0, s[54:55]
	global_load_lds_dwordx4 v[192:193], off
	v_cndmask_b32_e64 v173, v113, v121, s[2:3]
	v_cndmask_b32_e64 v172, v112, v120, s[2:3]
	v_cndmask_b32_e64 v177, v121, v113, s[2:3]
	v_cndmask_b32_e64 v176, v120, v112, s[2:3]
	s_waitcnt lgkmcnt(3)
	v_mfma_f32_32x32x16_bf16 v[64:79], v[228:231], v[88:91], v[64:79]
	ds_read_b128 v[228:231], v194 offset:128
	s_mov_b64 s[54:55], 0xe406000
	s_add_i32 m0, s96, 0xa000
	v_lshl_add_u64 v[192:193], v[134:135], 0, s[54:55]
	global_load_lds_dwordx4 v[192:193], off
	v_cndmask_b32_e64 v171, v119, v127, s[2:3]
	v_cndmask_b32_e64 v170, v118, v126, s[2:3]
	v_cndmask_b32_e64 v169, v117, v125, s[2:3]
	v_cndmask_b32_e64 v168, v116, v124, s[2:3]
	s_waitcnt lgkmcnt(3)
	v_mfma_f32_32x32x16_bf16 v[64:79], v[184:187], v[92:95], v[64:79]
	ds_read_b128 v[184:187], v195 offset:128
	s_mov_b64 s[54:55], 0xe804000
	s_add_i32 m0, s96, 0xc000
	v_lshl_add_u64 v[192:193], v[134:135], 0, s[54:55]
	global_load_lds_dwordx4 v[192:193], off
	v_cndmask_b32_e64 v175, v115, v123, s[2:3]
	v_cndmask_b32_e64 v174, v114, v122, s[2:3]
	v_cndmask_b32_e64 v127, v127, v119, s[2:3]
	v_cndmask_b32_e64 v126, v126, v118, s[2:3]
	s_waitcnt lgkmcnt(3)
	v_mfma_f32_32x32x16_bf16 v[64:79], v[180:183], v[96:99], v[64:79]
	ds_read_b64_tr_b16 v[180:181], v158 offset:0
	ds_read_b64_tr_b16 v[182:183], v158 offset:0x800
	s_mov_b64 s[54:55], 0xe806000
	s_add_i32 m0, s96, 0xe000
	v_lshl_add_u64 v[192:193], v[134:135], 0, s[54:55]
	global_load_lds_dwordx4 v[192:193], off
	v_cndmask_b32_e64 v125, v125, v117, s[2:3]
	v_cndmask_b32_e64 v124, v124, v116, s[2:3]
	v_cndmask_b32_e64 v179, v123, v115, s[2:3]
	v_cndmask_b32_e64 v178, v122, v114, s[2:3]
	s_waitcnt lgkmcnt(4)
	v_mfma_f32_32x32x16_bf16 v[64:79], v[188:191], v[100:103], v[64:79]
	s_cmp_gt_i32 s19, s18
	s_cbranch_scc1 .Li0_kskip
	v_lshl_add_u64 v[192:193], s[50:51], 0, v[130:131]
	s_mov_b64 s[54:55], 0xc408000
	s_mov_b32 m0, s97
	v_lshl_add_u64 v[192:193], v[192:193], 0, s[54:55]
	global_load_lds_dwordx4 v[192:193], off
	v_lshl_add_u64 v[192:193], s[50:51], 0, v[130:131]
	s_mov_b64 s[54:55], 0xc40a000
	s_mov_b32 m0, s26
	v_lshl_add_u64 v[192:193], v[192:193], 0, s[54:55]
	global_load_lds_dwordx4 v[192:193], off

.Li1_entry:
	ds_read_b128 v[64:67], v148
	ds_read_b128 v[188:191], v150
	ds_read_b128 v[228:231], v152
	ds_read_b128 v[184:187], v154
	ds_read_b128 v[180:183], v148 offset:128
	s_waitcnt lgkmcnt(4)
	v_mfma_f32_32x32x16_bf16 v[64:79], v[64:67], v[80:83], 0
	s_waitcnt lgkmcnt(3)
	v_mfma_f32_32x32x16_bf16 v[64:79], v[188:191], v[84:87], v[64:79]
	ds_read_b128 v[188:191], v150 offset:128
	s_mov_b64 s[56:57], 0xe408000
	s_mov_b32 m0, s96
	v_lshl_add_u64 v[192:193], v[134:135], 0, s[56:57]
	global_load_lds_dwordx4 v[192:193], off
	v_cndmask_b32_e64 v173, v113, v121, s[2:3]
	v_cndmask_b32_e64 v172, v112, v120, s[2:3]
	v_cndmask_b32_e64 v177, v121, v113, s[2:3]
	v_cndmask_b32_e64 v176, v120, v112, s[2:3]
	s_waitcnt lgkmcnt(3)
	v_mfma_f32_32x32x16_bf16 v[64:79], v[228:231], v[88:91], v[64:79]
	ds_read_b128 v[228:231], v152 offset:128
	s_mov_b64 s[56:57], 0xe40a000
	s_mov_b32 m0, s6
	v_lshl_add_u64 v[192:193], v[134:135], 0, s[56:57]
	global_load_lds_dwordx4 v[192:193], off
	v_cndmask_b32_e64 v171, v127, v119, s[2:3]
	v_cndmask_b32_e64 v170, v126, v118, s[2:3]
	v_cndmask_b32_e64 v169, v125, v117, s[2:3]
	v_cndmask_b32_e64 v168, v124, v116, s[2:3]
	s_waitcnt lgkmcnt(3)
	v_mfma_f32_32x32x16_bf16 v[64:79], v[184:187], v[92:95], v[64:79]
	ds_read_b128 v[184:187], v154 offset:128
	s_mov_b64 s[56:57], 0xe808000
	s_mov_b32 m0, s7
	v_lshl_add_u64 v[192:193], v[134:135], 0, s[56:57]
	global_load_lds_dwordx4 v[192:193], off
	v_cndmask_b32_e64 v175, v115, v123, s[2:3]
	v_cndmask_b32_e64 v174, v114, v122, s[2:3]
	v_cndmask_b32_e64 v127, v119, v127, s[2:3]
	v_cndmask_b32_e64 v126, v118, v126, s[2:3]
	s_waitcnt lgkmcnt(3)
	v_mfma_f32_32x32x16_bf16 v[64:79], v[180:183], v[96:99], v[64:79]
	ds_read_b64_tr_b16 v[180:181], v158 offset:0x8000
	ds_read_b64_tr_b16 v[182:183], v158 offset:0x8800
	s_mov_b64 s[56:57], 0xe80a000
	s_mov_b32 m0, s24
	v_lshl_add_u64 v[192:193], v[134:135], 0, s[56:57]
	global_load_lds_dwordx4 v[192:193], off
	v_cndmask_b32_e64 v125, v117, v125, s[2:3]
	v_cndmask_b32_e64 v124, v116, v124, s[2:3]
	v_cndmask_b32_e64 v179, v123, v115, s[2:3]
	v_cndmask_b32_e64 v178, v122, v114, s[2:3]
	s_waitcnt lgkmcnt(4)
	v_mfma_f32_32x32x16_bf16 v[64:79], v[188:191], v[100:103], v[64:79]
	s_add_i32 s56, s19, 1
	s_cmp_gt_i32 s56, s18
	s_cbranch_scc1 .Li1_kskip
	v_lshl_add_u64 v[192:193], s[50:51], 0, v[130:131]
	s_mov_b64 s[56:57], 0xc40c000
	s_mov_b32 m0, s27
	v_lshl_add_u64 v[192:193], v[192:193], 0, s[56:57]
	global_load_lds_dwordx4 v[192:193], off
	v_lshl_add_u64 v[192:193], s[50:51], 0, v[130:131]
	s_mov_b64 s[56:57], 0xc40e000
	s_mov_b32 m0, s62
	v_lshl_add_u64 v[192:193], v[192:193], 0, s[56:57]
	global_load_lds_dwordx4 v[192:193], off
